# gatenorm rows re-split 1 per wave (GEMM-quadrant workgroups) / 7 per wave (others) on top of the resident norm weights
# speedup vs baseline: 1.0021x; 1.0021x over previous
.LBB0_1137:
	s_andn2_b64 vcc, exec, s[0:1]
	s_cbranch_vccnz .LBB0_1205
	v_readlane_b32 s3, v246, 0
	s_cmp_gt_i32 s3, 31
	s_mov_b64 s[0:1], -1
	v_mov_b32_e32 v1, v180
	s_lshl_b32 s0, s3, 3
	s_mov_b32 s69, -1
	s_cmp_gt_u32 s3, 127
	s_mov_b32 s64, 0
	s_mov_b32 s65, 0xfffffc00
	s_cselect_b32 s69, 0x1bff, s69
	s_add_i32 s1, s0, s64
	v_ashrrev_i32_e32 v2, 6, v1
	v_add_u32_e32 v0, s1, v2
	v_cmp_gt_i32_e32 vcc, s87, v0
	s_and_saveexec_b64 s[8:9], vcc
	s_mov_b32 s15, 0xe900000
	s_mov_b32 s20, 0x10d03000
	s_mov_b32 s34, 0x358637bd
	s_mov_b32 s36, 0x3b800000
	s_brev_b32 s40, 60
	s_cbranch_execz .LBB0_1142
	v_and_b32_e32 v4, 64, v182
	v_xor_b32_e32 v3, 1, v182
	v_add_u32_e32 v4, 64, v4
	v_cmp_lt_i32_e32 vcc, v3, v4
	s_lshl_b64 s[6:7], s[24:25], 2
	s_add_u32 s6, s2, s6
	v_cndmask_b32_e32 v3, v182, v3, vcc
	v_lshlrev_b32_e32 v88, 2, v3
	v_xor_b32_e32 v3, 2, v182
	v_cmp_lt_i32_e32 vcc, v3, v4
	s_addc_u32 s7, s4, s7
	v_add_u32_e32 v2, s0, v2
	v_cndmask_b32_e32 v3, v182, v3, vcc
	v_lshlrev_b32_e32 v89, 2, v3
	v_xor_b32_e32 v3, 4, v182
	v_cmp_lt_i32_e32 vcc, v3, v4
	v_add_u32_e32 v93, s65, v2
	s_mov_b64 s[12:13], 0
	v_cndmask_b32_e32 v3, v182, v3, vcc
	v_lshlrev_b32_e32 v90, 2, v3
	v_xor_b32_e32 v3, 8, v182
	v_cmp_lt_i32_e32 vcc, v3, v4
	s_nop 1
	v_cndmask_b32_e32 v3, v182, v3, vcc
	v_lshlrev_b32_e32 v91, 2, v3
	v_xor_b32_e32 v3, 16, v182
	v_cmp_lt_i32_e32 vcc, v3, v4
	s_nop 1
	v_cndmask_b32_e32 v3, v182, v3, vcc
	v_lshlrev_b32_e32 v92, 2, v3
	v_lshlrev_b32_e32 v3, 5, v1
	v_and_b32_e32 v144, 0x1e0, v3
	v_lshl_add_u64 v[8:9], s[6:7], 0, v[144:145]
	s_lshl_b64 s[6:7], s[38:39], 2
	s_add_u32 s4, s5, s6
	s_addc_u32 s5, s14, s7
	v_and_b32_e32 v144, 0x3e0, v3
	v_and_b32_e32 v1, 63, v1
	v_lshl_add_u64 v[10:11], s[4:5], 0, v[144:145]
	v_lshlrev_b32_e32 v144, 4, v1
	v_ashrrev_i32_e32 v1, 31, v0
	v_mov_b64_e32 v[2:3], s[26:27]
	v_mad_i64_i32 v[12:13], s[0:1], v0, s86, v[2:3]
	v_lshlrev_b64 v[0:1], 12, v[0:1]
	v_lshl_add_u64 v[14:15], s[26:27], 0, v[0:1]
	flat_load_dwordx4 v[190:193], v[8:9]
	flat_load_dwordx4 v[194:197], v[8:9] offset:16
	flat_load_dwordx4 v[198:201], v[10:11]
	flat_load_dwordx4 v[202:205], v[10:11] offset:16
	s_waitcnt vmcnt(0) lgkmcnt(0)
